# scan helper waves: operand loads of the next fill issued at the end of the current fill (software-pipelined), block-internal vmcnt waits dropped
# baseline (speedup 1.0000x reference)
.LBB0_139:
	s_or_b64 exec, exec, s[12:13]
	s_lshl_b32 s0, s14, 2
	s_and_b32 s0, s0, 0x80
	v_lshl_or_b32 v2, v90, 2, s0
	s_lshl_b32 s0, s24, 2
	v_readlane_b32 s10, v254, 18
	s_and_b32 s0, s0, 32
	v_lshlrev_b64 v[0:1], 1, v[0:1]
	v_readlane_b32 s11, v254, 19
	v_lshl_add_u64 v[60:61], v[54:55], 0, v[0:1]
	v_lshl_add_u64 v[62:63], v[56:57], 0, v[0:1]
	v_lshl_add_u64 v[0:1], s[10:11], 0, v[0:1]
	s_lshl_b32 s26, s0, 1
	v_lshl_add_u64 v[0:1], v[0:1], 0, s[26:27]
	v_or_b32_e32 v98, 0xb00, v2
	v_or_b32_e32 v99, 0x6b00, v2
	v_mov_b32_e32 v2, v149
	v_mov_b32_e32 v3, v149
	v_lshl_add_u64 v[66:67], v[0:1], 0, v[148:149]
	v_mov_b32_e32 v0, v149
	v_mov_b32_e32 v1, v149
	v_mov_b64_e32 v[6:7], v[2:3]
	v_or_b32_e32 v59, s0, v90
	v_lshl_add_u64 v[64:65], s[38:39], 0, v[52:53]
	s_mov_b32 s25, 0
	s_mov_b64 s[40:41], 0
	v_mov_b64_e32 v[4:5], v[0:1]
	s_and_saveexec_b64 s[12:13], s[8:9]
	v_mov_b32_e32 v0, v91
	v_ashrrev_i32_e32 v1, 31, v0
	v_lshl_add_u64 v[0:1], s[38:39], 0, v[0:1]
	v_mad_u64_u32 v[2:3], vcc, v0, s75, v[60:61]
	v_mad_i32_i24 v3, v1, s75, v3
	v_mad_u64_u32 v[6:7], vcc, v0, s89, v[62:63]
	v_mad_i32_i24 v7, v1, s89, v7
	v_mov_b32_e32 v4, v178
	v_mov_b32_e32 v5, -1
	v_lshl_add_u64 v[4:5], v[2:3], 0, v[4:5]
	global_load_dwordx2 v[104:105], v[2:3], off
	global_load_dwordx2 v[106:107], v[2:3], off offset:1536
	global_load_dwordx2 v[108:109], v[2:3], off offset:3072
	global_load_dwordx2 v[110:111], v[4:5], off
	global_load_dwordx2 v[112:113], v[4:5], off offset:1536
	global_load_dwordx2 v[114:115], v[4:5], off offset:3072
	global_load_dwordx2 v[116:117], v[6:7], off
	global_load_dwordx2 v[118:119], v[6:7], off offset:1536
	s_waitcnt vmcnt(0)
	s_mov_b64 exec, s[12:13]
	s_waitcnt lgkmcnt(0)
	s_barrier
	s_branch .LBB0_141

.LBB0_141:
	s_and_b32 s45, s25, 1
	s_xor_b32 s44, s45, 1
	s_cmpk_lg_i32 s25, 0x7f
	s_cselect_b64 s[10:11], -1, 0
	s_lshl_b32 s26, s25, 5
	v_cndmask_b32_e64 v8, 0, 1, s[10:11]
	s_mul_i32 s44, s44, 0xc000
	v_add_u32_e32 v68, s26, v91
	v_cmp_ne_u32_e64 s[10:11], 1, v8
	s_and_saveexec_b64 s[12:13], s[8:9]
	s_xor_b64 s[42:43], exec, s[12:13]
	s_cbranch_execz .LBB0_144
	s_and_b64 vcc, exec, s[10:11]
	s_cbranch_vccnz .LBB0_144
	v_ashrrev_i32_e32 v69, 31, v68
	v_lshl_add_u64 v[8:9], s[38:39], 0, v[68:69]
	v_cmp_lt_i32_e32 vcc, 0, v68
	v_mad_u64_u32 v[10:11], s[12:13], v8, s75, v[60:61]
	v_mad_i32_i24 v11, v9, s75, v11
	v_cndmask_b32_e64 v35, 0, -1, vcc
	v_cndmask_b32_e32 v34, 0, v178, vcc
	v_lshl_add_u64 v[12:13], v[10:11], 0, v[34:35]
	s_waitcnt vmcnt(1)
	v_mov_b32_e32 v36, v104
	v_mov_b32_e32 v37, v105
	v_mov_b32_e32 v38, v106
	v_mov_b32_e32 v39, v107
	v_mov_b32_e32 v72, v108
	v_mov_b32_e32 v73, v109
	v_mov_b32_e32 v74, v110
	v_mov_b32_e32 v75, v111
	v_mov_b32_e32 v76, v112
	v_mov_b32_e32 v77, v113
	v_mov_b32_e32 v78, v114
	v_mov_b32_e32 v79, v115
	v_mad_u64_u32 v[10:11], s[12:13], v8, s89, v[62:63]
	v_mad_i32_i24 v11, v9, s89, v11
	v_mov_b32_e32 v22, v116
	v_mov_b32_e32 v23, v117
	v_mov_b32_e32 v24, v118
	v_mov_b32_e32 v25, v119
	ds_read_b128 v[16:19], v84
	ds_read_b128 v[26:29], v85
	ds_read_b128 v[12:15], v86
	ds_read_b128 v[30:33], v87
	ds_read_b128 v[8:11], v88
	v_lshlrev_b32_e32 v80, 16, v72
	v_and_b32_e32 v81, 0xffff0000, v72
	v_lshlrev_b32_e32 v72, 16, v73
	v_and_b32_e32 v69, v78, v35
	v_and_b32_e32 v34, v79, v35
	v_lshlrev_b32_e32 v78, 16, v69
	v_and_b32_e32 v79, 0xffff0000, v69
	v_pk_add_f32 v[78:79], v[78:79], v[80:81] neg_lo:[0,1] neg_hi:[0,1]
	v_and_b32_e32 v73, 0xffff0000, v73
	s_waitcnt lgkmcnt(2)
	v_pk_fma_f32 v[12:13], v[78:79], v[12:13], v[80:81]
	v_lshlrev_b32_e32 v78, 16, v34
	v_and_b32_e32 v79, 0xffff0000, v34
	v_pk_add_f32 v[78:79], v[78:79], v[72:73] neg_lo:[0,1] neg_hi:[0,1]
	v_and_b32_e32 v69, v77, v35
	v_and_b32_e32 v70, v76, v35
	v_and_b32_e32 v75, v75, v35
	v_and_b32_e32 v35, v74, v35
	v_pk_fma_f32 v[14:15], v[78:79], v[14:15], v[72:73]
	v_lshlrev_b32_e32 v34, 16, v35
	v_and_b32_e32 v35, 0xffff0000, v35
	v_lshlrev_b32_e32 v72, 16, v36
	v_and_b32_e32 v73, 0xffff0000, v36
	v_pk_add_f32 v[34:35], v[34:35], v[72:73] neg_lo:[0,1] neg_hi:[0,1]
	v_lshlrev_b32_e32 v36, 16, v37
	v_pk_fma_f32 v[16:17], v[34:35], v[16:17], v[72:73]
	v_lshlrev_b32_e32 v34, 16, v75
	v_and_b32_e32 v35, 0xffff0000, v75
	v_and_b32_e32 v37, 0xffff0000, v37
	v_pk_add_f32 v[34:35], v[34:35], v[36:37] neg_lo:[0,1] neg_hi:[0,1]
	v_lshlrev_b32_e32 v20, 16, v22
	v_pk_fma_f32 v[18:19], v[34:35], v[18:19], v[36:37]
	v_lshlrev_b32_e32 v34, 16, v70
	v_and_b32_e32 v35, 0xffff0000, v70
	v_lshlrev_b32_e32 v36, 16, v38
	v_and_b32_e32 v37, 0xffff0000, v38
	v_pk_add_f32 v[34:35], v[34:35], v[36:37] neg_lo:[0,1] neg_hi:[0,1]
	v_lshlrev_b32_e32 v38, 16, v39
	v_pk_fma_f32 v[26:27], v[34:35], v[26:27], v[36:37]
	v_lshlrev_b32_e32 v36, 16, v69
	v_and_b32_e32 v37, 0xffff0000, v69
	v_and_b32_e32 v39, 0xffff0000, v39
	v_pk_add_f32 v[36:37], v[36:37], v[38:39] neg_lo:[0,1] neg_hi:[0,1]
	s_waitcnt lgkmcnt(1)
	v_pk_mul_f32 v[30:31], v[30:31], v[26:27]
	v_pk_fma_f32 v[28:29], v[36:37], v[28:29], v[38:39]
	v_pk_mul_f32 v[34:35], v[30:31], v[30:31]
	v_pk_mul_f32 v[32:33], v[32:33], v[28:29]
	v_add_f32_e32 v34, v34, v35
	v_pk_mul_f32 v[36:37], v[32:33], v[32:33]
	v_and_b32_e32 v21, 0xffff0000, v22
	v_add_f32_e32 v34, v36, v34
	v_add_f32_e32 v34, v37, v34
	v_lshlrev_b32_e32 v22, 16, v23
	v_and_b32_e32 v23, 0xffff0000, v23
	v_add_f32_dpp v34, v34, v34 row_ror:8 row_mask:0xf bank_mask:0xf bound_ctrl:1
	v_mul_f32_e32 v20, 0x3fb8aa3b, v20
	v_mul_f32_e32 v21, 0x3fb8aa3b, v21
	v_add_f32_dpp v34, v34, v34 row_ror:4 row_mask:0xf bank_mask:0xf bound_ctrl:1
	v_mul_f32_e32 v22, 0x3fb8aa3b, v22
	v_mul_f32_e32 v23, 0x3fb8aa3b, v23
	v_add_f32_dpp v34, v34, v34 row_ror:2 row_mask:0xf bank_mask:0xf bound_ctrl:1
	v_exp_f32_e32 v20, v20
	v_exp_f32_e32 v21, v21
	v_add_f32_dpp v34, v34, v34 row_ror:1 row_mask:0xf bank_mask:0xf bound_ctrl:1
	v_cmp_gt_f32_e32 vcc, s95, v34
	v_mul_f32_e32 v35, 0x4f800000, v34
	v_exp_f32_e32 v22, v22
	v_cndmask_b32_e32 v34, v34, v35, vcc
	v_sqrt_f32_e32 v35, v34
	v_exp_f32_e32 v23, v23
	v_add_u32_e32 v36, -1, v35
	v_fma_f32 v37, -v36, v35, v34
	v_cmp_ge_f32_e64 s[12:13], 0, v37
	v_add_u32_e32 v37, 1, v35
	s_nop 0
	v_cndmask_b32_e64 v36, v35, v36, s[12:13]
	v_fma_f32 v35, -v37, v35, v34
	v_cmp_lt_f32_e64 s[12:13], 0, v35
	s_nop 1
	v_cndmask_b32_e64 v35, v36, v37, s[12:13]
	v_mul_f32_e32 v36, 0x37800000, v35
	v_cndmask_b32_e32 v35, v35, v36, vcc
	v_cmp_class_f32_e32 vcc, v34, v170
	s_nop 1
	v_cndmask_b32_e32 v34, v35, v34, vcc
	v_max_f32_e32 v34, 0x2b8cbccc, v34
	v_div_scale_f32 v35, s[12:13], v34, v34, 1.0
	v_rcp_f32_e32 v36, v35
	s_nop 0
	v_fma_f32 v37, -v35, v36, 1.0
	v_fmac_f32_e32 v36, v37, v36
	v_div_scale_f32 v37, vcc, 1.0, v34, 1.0
	v_mul_f32_e32 v38, v37, v36
	v_fma_f32 v39, -v35, v38, v37
	v_fmac_f32_e32 v38, v39, v36
	v_fma_f32 v35, -v35, v38, v37
	v_div_fmas_f32 v35, v35, v36, v38
	v_div_fixup_f32 v34, v35, v34, 1.0
	v_add_u32_e32 v35, s44, v93
	ds_write_b128 v35, v[20:23]
	v_pk_mul_f32 v[22:23], v[32:33], v[34:35] op_sel_hi:[1,0] neg_lo:[0,1] neg_hi:[0,1]
	v_pk_mul_f32 v[20:21], v[30:31], v[34:35] op_sel_hi:[1,0] neg_lo:[0,1] neg_hi:[0,1]
	ds_write_b128 v35, v[20:23] offset:256
	v_pk_mul_f32 v[20:21], v[30:31], v[34:35] op_sel_hi:[1,0]
	v_pk_mul_f32 v[22:23], v[32:33], v[34:35] op_sel_hi:[1,0]
	v_lshlrev_b32_e32 v30, 16, v24
	v_and_b32_e32 v31, 0xffff0000, v24
	v_lshlrev_b32_e32 v24, 16, v25
	v_and_b32_e32 v25, 0xffff0000, v25
	v_pk_mul_f32 v[22:23], v[22:23], v[24:25]
	v_pk_mul_f32 v[20:21], v[20:21], v[30:31]
	ds_write_b128 v35, v[20:23] offset:512
	v_pk_add_f32 v[20:21], v[24:25], -1.0 op_sel_hi:[1,0]
	v_pk_add_f32 v[22:23], v[30:31], -1.0 op_sel_hi:[1,0]
	s_waitcnt lgkmcnt(3)
	v_pk_fma_f32 v[10:11], v[20:21], v[10:11], 1.0 op_sel_hi:[1,1,0]
	v_pk_fma_f32 v[8:9], v[22:23], v[8:9], 1.0 op_sel_hi:[1,1,0]
	v_pk_mul_f32 v[10:11], v[28:29], v[10:11]
	v_pk_mul_f32 v[8:9], v[26:27], v[8:9]
	ds_write_b128 v35, v[8:11] offset:768
	ds_write_b128 v35, v[16:19] offset:1024
	ds_write_b128 v35, v[12:15] offset:1280
	v_add_u32_e32 v0, s26, v91
	v_add_u32_e32 v0, 16, v0
	v_ashrrev_i32_e32 v1, 31, v0
	v_lshl_add_u64 v[0:1], s[38:39], 0, v[0:1]
	v_mad_u64_u32 v[2:3], vcc, v0, s75, v[60:61]
	v_mad_i32_i24 v3, v1, s75, v3
	v_mad_u64_u32 v[6:7], vcc, v0, s89, v[62:63]
	v_mad_i32_i24 v7, v1, s89, v7
	v_mov_b32_e32 v4, v178
	v_mov_b32_e32 v5, -1
	v_lshl_add_u64 v[4:5], v[2:3], 0, v[4:5]
	global_load_dwordx2 v[104:105], v[2:3], off
	global_load_dwordx2 v[106:107], v[2:3], off offset:1536
	global_load_dwordx2 v[108:109], v[2:3], off offset:3072
	global_load_dwordx2 v[110:111], v[4:5], off
	global_load_dwordx2 v[112:113], v[4:5], off offset:1536
	global_load_dwordx2 v[114:115], v[4:5], off offset:3072
	global_load_dwordx2 v[116:117], v[6:7], off
	global_load_dwordx2 v[118:119], v[6:7], off offset:1536

.LBB0_148:
	s_or_b64 exec, exec, s[12:13]
	s_waitcnt lgkmcnt(0)
	s_barrier
	ds_read_b128 v[8:11], v97
	ds_read_b128 v[12:15], v97 offset:32
	ds_read_b128 v[16:19], v97 offset:16
	ds_read_b128 v[20:23], v97 offset:48
	s_waitcnt lgkmcnt(3)
	v_mov_b32_e32 v24, v8
	s_waitcnt lgkmcnt(2)
	v_mov_b32_e32 v25, v12
	v_mov_b32_e32 v12, v9
	v_pk_add_f32 v[8:9], v[24:25], v[12:13]
	v_mov_b32_e32 v12, v10
	v_mov_b32_e32 v13, v14
	v_mov_b32_e32 v14, v11
	v_pk_add_f32 v[10:11], v[12:13], v[14:15]
	s_waitcnt lgkmcnt(1)
	v_mov_b32_e32 v12, v18
	v_pk_add_f32 v[8:9], v[8:9], v[10:11]
	v_mov_b32_e32 v10, v16
	s_waitcnt lgkmcnt(0)
	v_mov_b32_e32 v11, v20
	v_mov_b32_e32 v20, v17
	v_mov_b32_e32 v13, v22
	v_mov_b32_e32 v22, v19
	v_pk_add_f32 v[10:11], v[10:11], v[20:21]
	v_pk_add_f32 v[12:13], v[12:13], v[22:23]
	s_nop 0
	v_pk_add_f32 v[10:11], v[10:11], v[12:13]
	s_nop 0
	v_pk_add_f32 v[8:9], v[8:9], v[10:11]
	s_nop 0
	v_add_f32_e32 v8, v8, v9
	v_cvt_pk_bf16_f32 v12, v8, v149
	v_lshl_add_u64 v[8:9], v[64:65], 0, s[26:27]
	v_mad_u64_u32 v[10:11], s[12:13], v8, s74, v[66:67]
	v_mad_i32_i24 v11, v9, s74, v11
	global_store_short v[10:11], v12, off
	s_barrier
	s_and_saveexec_b64 s[12:13], s[8:9]
	s_xor_b64 s[12:13], exec, s[12:13]
	s_cbranch_execz .LBB0_151
	s_and_b64 vcc, exec, s[10:11]
	s_cbranch_vccnz .LBB0_151
	v_add_u32_e32 v8, 16, v68
	v_ashrrev_i32_e32 v9, 31, v8
	v_lshl_add_u64 v[8:9], s[38:39], 0, v[8:9]
	v_mad_u64_u32 v[10:11], s[10:11], v8, s75, v[60:61]
	v_mad_u64_u32 v[34:35], s[10:11], v8, s89, v[62:63]
	v_cmp_lt_i32_e32 vcc, -16, v68
	v_mad_i32_i24 v11, v9, s75, v11
	v_mad_i32_i24 v35, v9, s89, v35
	v_cndmask_b32_e64 v39, 0, -1, vcc
	v_cndmask_b32_e32 v38, 0, v178, vcc
	s_waitcnt vmcnt(1)
	v_mov_b32_e32 v28, v108
	v_mov_b32_e32 v29, v109
	v_mov_b32_e32 v30, v104
	v_mov_b32_e32 v31, v105
	v_mov_b32_e32 v32, v106
	v_mov_b32_e32 v33, v107
	v_mov_b32_e32 v36, v116
	v_mov_b32_e32 v37, v117
	v_lshl_add_u64 v[8:9], v[10:11], 0, v[38:39]
	v_mov_b32_e32 v68, v114
	v_mov_b32_e32 v69, v115
	v_mov_b32_e32 v72, v112
	v_mov_b32_e32 v73, v113
	v_mov_b32_e32 v74, v110
	v_mov_b32_e32 v75, v111
	ds_read_b128 v[12:15], v84
	ds_read_b128 v[16:19], v85
	ds_read_b128 v[20:23], v86
	ds_read_b128 v[24:27], v87
	ds_read_b128 v[8:11], v88
	v_mov_b32_e32 v34, v118
	v_mov_b32_e32 v35, v119
	v_add_u32_e32 v70, s44, v93
	v_lshlrev_b32_e32 v76, 16, v28
	v_lshlrev_b32_e32 v80, 16, v30
	v_and_b32_e32 v81, 0xffff0000, v30
	v_lshlrev_b32_e32 v82, 16, v31
	v_and_b32_e32 v83, 0xffff0000, v31
	v_lshlrev_b32_e32 v30, 16, v37
	v_and_b32_e32 v31, 0xffff0000, v37
	v_and_b32_e32 v37, v68, v39
	v_and_b32_e32 v102, v72, v39
	v_and_b32_e32 v77, 0xffff0000, v28
	v_lshlrev_b32_e32 v78, 16, v29
	v_and_b32_e32 v79, 0xffff0000, v29
	v_lshlrev_b32_e32 v100, 16, v32
	v_and_b32_e32 v101, 0xffff0000, v32
	v_lshlrev_b32_e32 v28, 16, v36
	v_and_b32_e32 v29, 0xffff0000, v36
	v_and_b32_e32 v103, v73, v39
	v_and_b32_e32 v73, v75, v39
	v_and_b32_e32 v72, v74, v39
	v_lshlrev_b32_e32 v36, 16, v37
	v_and_b32_e32 v37, 0xffff0000, v37
	v_lshlrev_b32_e32 v74, 16, v102
	v_and_b32_e32 v75, 0xffff0000, v102
	v_lshlrev_b32_e32 v32, 16, v33
	v_and_b32_e32 v33, 0xffff0000, v33
	v_lshlrev_b32_e32 v102, 16, v103
	v_and_b32_e32 v103, 0xffff0000, v103
	v_pk_add_f32 v[36:37], v[36:37], v[76:77] neg_lo:[0,1] neg_hi:[0,1]
	v_pk_add_f32 v[74:75], v[74:75], v[100:101] neg_lo:[0,1] neg_hi:[0,1]
	v_pk_add_f32 v[102:103], v[102:103], v[32:33] neg_lo:[0,1] neg_hi:[0,1]
	s_waitcnt lgkmcnt(2)
	v_pk_fma_f32 v[20:21], v[36:37], v[20:21], v[76:77]
	v_pk_fma_f32 v[36:37], v[74:75], v[16:17], v[100:101]
	v_pk_fma_f32 v[32:33], v[102:103], v[18:19], v[32:33]
	s_waitcnt lgkmcnt(1)
	v_pk_mul_f32 v[24:25], v[24:25], v[36:37]
	v_pk_mul_f32 v[26:27], v[26:27], v[32:33]
	v_pk_mul_f32 v[16:17], v[24:25], v[24:25]
	v_pk_mul_f32 v[18:19], v[26:27], v[26:27]
	v_add_f32_e32 v16, v16, v17
	v_add_f32_e32 v16, v18, v16
	v_add_f32_e32 v16, v19, v16
	v_and_b32_e32 v69, v69, v39
	v_lshlrev_b32_e32 v38, 16, v69
	v_add_f32_dpp v16, v16, v16 row_ror:8 row_mask:0xf bank_mask:0xf bound_ctrl:1
	v_and_b32_e32 v39, 0xffff0000, v69
	v_pk_add_f32 v[38:39], v[38:39], v[78:79] neg_lo:[0,1] neg_hi:[0,1]
	v_add_f32_dpp v16, v16, v16 row_ror:4 row_mask:0xf bank_mask:0xf bound_ctrl:1
	v_pk_fma_f32 v[22:23], v[38:39], v[22:23], v[78:79]
	v_mul_f32_e32 v28, 0x3fb8aa3b, v28
	v_add_f32_dpp v16, v16, v16 row_ror:2 row_mask:0xf bank_mask:0xf bound_ctrl:1
	v_mul_f32_e32 v29, 0x3fb8aa3b, v29
	v_mul_f32_e32 v30, 0x3fb8aa3b, v30
	v_add_f32_dpp v16, v16, v16 row_ror:1 row_mask:0xf bank_mask:0xf bound_ctrl:1
	v_mul_f32_e32 v17, 0x4f800000, v16
	v_cmp_gt_f32_e32 vcc, s95, v16
	v_mul_f32_e32 v31, 0x3fb8aa3b, v31
	v_exp_f32_e32 v28, v28
	v_cndmask_b32_e32 v16, v16, v17, vcc
	v_sqrt_f32_e32 v17, v16
	v_exp_f32_e32 v29, v29
	v_exp_f32_e32 v30, v30
	v_exp_f32_e32 v31, v31
	v_add_u32_e32 v18, -1, v17
	v_add_u32_e32 v19, 1, v17
	v_fma_f32 v38, -v18, v17, v16
	v_fma_f32 v39, -v19, v17, v16
	v_cmp_ge_f32_e64 s[10:11], 0, v38
	ds_write_b128 v70, v[28:31] offset:24576
	v_lshlrev_b32_e32 v68, 16, v72
	v_cndmask_b32_e64 v17, v17, v18, s[10:11]
	v_cmp_lt_f32_e64 s[10:11], 0, v39
	v_and_b32_e32 v69, 0xffff0000, v72
	v_lshlrev_b32_e32 v72, 16, v73
	v_cndmask_b32_e64 v17, v17, v19, s[10:11]
	v_mul_f32_e32 v18, 0x37800000, v17
	v_cndmask_b32_e32 v17, v17, v18, vcc
	v_cmp_class_f32_e32 vcc, v16, v170
	v_and_b32_e32 v73, 0xffff0000, v73
	v_pk_add_f32 v[68:69], v[68:69], v[80:81] neg_lo:[0,1] neg_hi:[0,1]
	v_cndmask_b32_e32 v16, v17, v16, vcc
	v_max_f32_e32 v16, 0x2b8cbccc, v16
	v_div_scale_f32 v17, s[10:11], v16, v16, 1.0
	v_rcp_f32_e32 v18, v17
	v_div_scale_f32 v19, vcc, 1.0, v16, 1.0
	v_pk_add_f32 v[72:73], v[72:73], v[82:83] neg_lo:[0,1] neg_hi:[0,1]
	v_fma_f32 v28, -v17, v18, 1.0
	v_fmac_f32_e32 v18, v28, v18
	v_mul_f32_e32 v28, v19, v18
	v_fma_f32 v29, -v17, v28, v19
	v_fmac_f32_e32 v28, v29, v18
	v_fma_f32 v17, -v17, v28, v19
	v_div_fmas_f32 v17, v17, v18, v28
	v_div_fixup_f32 v28, v17, v16, 1.0
	v_pk_mul_f32 v[18:19], v[26:27], v[28:29] op_sel_hi:[1,0] neg_lo:[0,1] neg_hi:[0,1]
	v_pk_mul_f32 v[16:17], v[24:25], v[28:29] op_sel_hi:[1,0] neg_lo:[0,1] neg_hi:[0,1]
	v_pk_mul_f32 v[24:25], v[24:25], v[28:29] op_sel_hi:[1,0]
	ds_write_b128 v70, v[16:19] offset:24832
	v_pk_mul_f32 v[16:17], v[26:27], v[28:29] op_sel_hi:[1,0]
	v_lshlrev_b32_e32 v26, 16, v34
	v_and_b32_e32 v27, 0xffff0000, v34
	v_lshlrev_b32_e32 v28, 16, v35
	v_and_b32_e32 v29, 0xffff0000, v35
	v_pk_mul_f32 v[18:19], v[16:17], v[28:29]
	v_pk_mul_f32 v[16:17], v[24:25], v[26:27]
	ds_write_b128 v70, v[16:19] offset:25088
	v_pk_add_f32 v[16:17], v[28:29], -1.0 op_sel_hi:[1,0]
	v_pk_add_f32 v[18:19], v[26:27], -1.0 op_sel_hi:[1,0]
	s_waitcnt lgkmcnt(3)
	v_pk_fma_f32 v[10:11], v[16:17], v[10:11], 1.0 op_sel_hi:[1,1,0]
	v_pk_fma_f32 v[8:9], v[18:19], v[8:9], 1.0 op_sel_hi:[1,1,0]
	v_pk_mul_f32 v[10:11], v[32:33], v[10:11]
	v_pk_mul_f32 v[8:9], v[36:37], v[8:9]
	v_pk_fma_f32 v[12:13], v[68:69], v[12:13], v[80:81]
	v_pk_fma_f32 v[14:15], v[72:73], v[14:15], v[82:83]
	ds_write_b128 v70, v[8:11] offset:25344
	ds_write_b128 v70, v[12:15] offset:25600
	ds_write_b128 v70, v[20:23] offset:25856
	s_cmp_lt_u32 s25, 126
	s_cbranch_scc0 .Lsf_skip
	v_add_u32_e32 v0, s26, v91
	v_add_u32_e32 v0, 32, v0
	v_ashrrev_i32_e32 v1, 31, v0
	v_lshl_add_u64 v[0:1], s[38:39], 0, v[0:1]
	v_mad_u64_u32 v[2:3], vcc, v0, s75, v[60:61]
	v_mad_i32_i24 v3, v1, s75, v3
	v_mad_u64_u32 v[6:7], vcc, v0, s89, v[62:63]
	v_mad_i32_i24 v7, v1, s89, v7
	v_mov_b32_e32 v4, v178
	v_mov_b32_e32 v5, -1
	v_lshl_add_u64 v[4:5], v[2:3], 0, v[4:5]
	global_load_dwordx2 v[104:105], v[2:3], off
	global_load_dwordx2 v[106:107], v[2:3], off offset:1536
	global_load_dwordx2 v[108:109], v[2:3], off offset:3072
	global_load_dwordx2 v[110:111], v[4:5], off
	global_load_dwordx2 v[112:113], v[4:5], off offset:1536
	global_load_dwordx2 v[114:115], v[4:5], off offset:3072
	global_load_dwordx2 v[116:117], v[6:7], off
	global_load_dwordx2 v[118:119], v[6:7], off offset:1536
.Lsf_skip:
.LBB0_151:
	s_andn2_saveexec_b64 s[10:11], s[12:13]
	s_cbranch_execz .LBB0_140
	v_bfe_u32 v119, v171, 4, 2
	v_lshl_add_u32 v118, v119, 2, v100
	v_lshl_add_u32 v119, v119, 6, v94
	v_add_u32_e32 v119, 0x18000, v119
	ds_read_b128 v[12:15], v69 offset:24832
	ds_read_b128 v[20:23], v69 offset:25344
	ds_read_b64 v[28:29], v118 offset:25856
	ds_read_b128 v[8:11], v69 offset:24576
	ds_read_b128 v[16:19], v69 offset:25088
	ds_read_b128 v[24:27], v69 offset:25600
	s_setprio 3
	s_waitcnt lgkmcnt(0)
	v_pk_mul_f32 v[110:111], v[0:1], v[12:13] op_sel_hi:[1,0]
	v_pk_mul_f32 v[38:39], v[28:29], v[20:21] op_sel_hi:[1,0]
	v_pk_fma_f32 v[110:111], v[2:3], v[12:13], v[110:111] op_sel:[0,1,0]
	v_pk_mul_f32 v[82:83], v[28:29], v[20:21] op_sel:[0,1]
	v_pk_fma_f32 v[110:111], v[4:5], v[14:15], v[110:111] op_sel_hi:[1,0,1]
	v_pk_mul_f32 v[116:117], v[28:29], v[22:23] op_sel_hi:[1,0]
	v_pk_fma_f32 v[110:111], v[6:7], v[14:15], v[110:111] op_sel:[0,1,0]
	v_pk_mul_f32 v[114:115], v[28:29], v[22:23] op_sel:[0,1]
	ds_read_b128 v[34:37], v69 offset:26368
	ds_read_b128 v[78:81], v69 offset:26880
	ds_read_b64 v[108:109], v118 offset:27392
	ds_read_b128 v[30:33], v69 offset:26112
	ds_read_b128 v[74:77], v69 offset:26624
	ds_read_b128 v[104:107], v69 offset:27136
	v_add_f32_dpp v110, v110, v110 row_ror:8 row_mask:0xf bank_mask:0xf bound_ctrl:1
	v_add_f32_dpp v111, v111, v111 row_ror:8 row_mask:0xf bank_mask:0xf bound_ctrl:1
	v_pk_fma_f32 v[38:39], v[0:1], v[8:9], v[38:39] op_sel_hi:[1,0,1]
	v_add_f32_dpp v110, v110, v110 row_ror:4 row_mask:0xf bank_mask:0xf bound_ctrl:1
	v_add_f32_dpp v111, v111, v111 row_ror:4 row_mask:0xf bank_mask:0xf bound_ctrl:1
	v_pk_fma_f32 v[82:83], v[2:3], v[8:9], v[82:83] op_sel:[0,1,0]
	v_add_f32_dpp v110, v110, v110 row_ror:2 row_mask:0xf bank_mask:0xf bound_ctrl:1
	v_add_f32_dpp v111, v111, v111 row_ror:2 row_mask:0xf bank_mask:0xf bound_ctrl:1
	v_pk_fma_f32 v[116:117], v[4:5], v[10:11], v[116:117] op_sel_hi:[1,0,1]
	v_add_f32_dpp v110, v110, v110 row_ror:1 row_mask:0xf bank_mask:0xf bound_ctrl:1
	v_add_f32_dpp v111, v111, v111 row_ror:1 row_mask:0xf bank_mask:0xf bound_ctrl:1
	v_pk_fma_f32 v[114:115], v[6:7], v[10:11], v[114:115] op_sel:[0,1,0]
	v_pk_fma_f32 v[0:1], v[110:111], v[16:17], v[38:39] op_sel_hi:[1,0,1]
	v_pk_fma_f32 v[2:3], v[110:111], v[16:17], v[82:83] op_sel:[0,1,0]
	v_pk_fma_f32 v[4:5], v[110:111], v[18:19], v[116:117] op_sel_hi:[1,0,1]
	v_pk_fma_f32 v[6:7], v[110:111], v[18:19], v[114:115] op_sel:[0,1,0]
	v_pk_mul_f32 v[112:113], v[0:1], v[24:25] op_sel_hi:[1,0]
	v_pk_fma_f32 v[112:113], v[2:3], v[24:25], v[112:113] op_sel:[0,1,0]
	v_pk_fma_f32 v[112:113], v[4:5], v[26:27], v[112:113] op_sel_hi:[1,0,1]
	v_pk_fma_f32 v[112:113], v[6:7], v[26:27], v[112:113] op_sel:[0,1,0]
	ds_write_b32 v119, v112 offset:0
	ds_write_b32 v119, v113 offset:64
	s_waitcnt lgkmcnt(2)
	v_pk_mul_f32 v[110:111], v[0:1], v[34:35] op_sel_hi:[1,0]
	v_pk_mul_f32 v[38:39], v[108:109], v[78:79] op_sel_hi:[1,0]
	v_pk_fma_f32 v[110:111], v[2:3], v[34:35], v[110:111] op_sel:[0,1,0]
	v_pk_mul_f32 v[82:83], v[108:109], v[78:79] op_sel:[0,1]
	v_pk_fma_f32 v[110:111], v[4:5], v[36:37], v[110:111] op_sel_hi:[1,0,1]
	v_pk_mul_f32 v[116:117], v[108:109], v[80:81] op_sel_hi:[1,0]
	v_pk_fma_f32 v[110:111], v[6:7], v[36:37], v[110:111] op_sel:[0,1,0]
	v_pk_mul_f32 v[114:115], v[108:109], v[80:81] op_sel:[0,1]
	ds_read_b128 v[12:15], v69 offset:27904
	ds_read_b128 v[20:23], v69 offset:28416
	ds_read_b64 v[28:29], v118 offset:28928
	ds_read_b128 v[8:11], v69 offset:27648
	ds_read_b128 v[16:19], v69 offset:28160
	ds_read_b128 v[24:27], v69 offset:28672
	v_add_f32_dpp v110, v110, v110 row_ror:8 row_mask:0xf bank_mask:0xf bound_ctrl:1
	v_add_f32_dpp v111, v111, v111 row_ror:8 row_mask:0xf bank_mask:0xf bound_ctrl:1
	v_pk_fma_f32 v[38:39], v[0:1], v[30:31], v[38:39] op_sel_hi:[1,0,1]
	v_add_f32_dpp v110, v110, v110 row_ror:4 row_mask:0xf bank_mask:0xf bound_ctrl:1
	v_add_f32_dpp v111, v111, v111 row_ror:4 row_mask:0xf bank_mask:0xf bound_ctrl:1
	v_pk_fma_f32 v[82:83], v[2:3], v[30:31], v[82:83] op_sel:[0,1,0]
	v_add_f32_dpp v110, v110, v110 row_ror:2 row_mask:0xf bank_mask:0xf bound_ctrl:1
	v_add_f32_dpp v111, v111, v111 row_ror:2 row_mask:0xf bank_mask:0xf bound_ctrl:1
	v_pk_fma_f32 v[116:117], v[4:5], v[32:33], v[116:117] op_sel_hi:[1,0,1]
	v_add_f32_dpp v110, v110, v110 row_ror:1 row_mask:0xf bank_mask:0xf bound_ctrl:1
	v_add_f32_dpp v111, v111, v111 row_ror:1 row_mask:0xf bank_mask:0xf bound_ctrl:1
	v_pk_fma_f32 v[114:115], v[6:7], v[32:33], v[114:115] op_sel:[0,1,0]
	v_pk_fma_f32 v[0:1], v[110:111], v[74:75], v[38:39] op_sel_hi:[1,0,1]
	v_pk_fma_f32 v[2:3], v[110:111], v[74:75], v[82:83] op_sel:[0,1,0]
	v_pk_fma_f32 v[4:5], v[110:111], v[76:77], v[116:117] op_sel_hi:[1,0,1]
	v_pk_fma_f32 v[6:7], v[110:111], v[76:77], v[114:115] op_sel:[0,1,0]
	v_pk_mul_f32 v[112:113], v[0:1], v[104:105] op_sel_hi:[1,0]
	v_pk_fma_f32 v[112:113], v[2:3], v[104:105], v[112:113] op_sel:[0,1,0]
	v_pk_fma_f32 v[112:113], v[4:5], v[106:107], v[112:113] op_sel_hi:[1,0,1]
	v_pk_fma_f32 v[112:113], v[6:7], v[106:107], v[112:113] op_sel:[0,1,0]
	ds_write_b32 v119, v112 offset:2048
	ds_write_b32 v119, v113 offset:2112
	s_waitcnt lgkmcnt(2)
	v_pk_mul_f32 v[110:111], v[0:1], v[12:13] op_sel_hi:[1,0]
	v_pk_mul_f32 v[38:39], v[28:29], v[20:21] op_sel_hi:[1,0]
	v_pk_fma_f32 v[110:111], v[2:3], v[12:13], v[110:111] op_sel:[0,1,0]
	v_pk_mul_f32 v[82:83], v[28:29], v[20:21] op_sel:[0,1]
	v_pk_fma_f32 v[110:111], v[4:5], v[14:15], v[110:111] op_sel_hi:[1,0,1]
	v_pk_mul_f32 v[116:117], v[28:29], v[22:23] op_sel_hi:[1,0]
	v_pk_fma_f32 v[110:111], v[6:7], v[14:15], v[110:111] op_sel:[0,1,0]
	v_pk_mul_f32 v[114:115], v[28:29], v[22:23] op_sel:[0,1]
	ds_read_b128 v[34:37], v69 offset:29440
	ds_read_b128 v[78:81], v69 offset:29952
	ds_read_b64 v[108:109], v118 offset:30464
	ds_read_b128 v[30:33], v69 offset:29184
	ds_read_b128 v[74:77], v69 offset:29696
	ds_read_b128 v[104:107], v69 offset:30208
	v_add_f32_dpp v110, v110, v110 row_ror:8 row_mask:0xf bank_mask:0xf bound_ctrl:1
	v_add_f32_dpp v111, v111, v111 row_ror:8 row_mask:0xf bank_mask:0xf bound_ctrl:1
	v_pk_fma_f32 v[38:39], v[0:1], v[8:9], v[38:39] op_sel_hi:[1,0,1]
	v_add_f32_dpp v110, v110, v110 row_ror:4 row_mask:0xf bank_mask:0xf bound_ctrl:1
	v_add_f32_dpp v111, v111, v111 row_ror:4 row_mask:0xf bank_mask:0xf bound_ctrl:1
	v_pk_fma_f32 v[82:83], v[2:3], v[8:9], v[82:83] op_sel:[0,1,0]
	v_add_f32_dpp v110, v110, v110 row_ror:2 row_mask:0xf bank_mask:0xf bound_ctrl:1
	v_add_f32_dpp v111, v111, v111 row_ror:2 row_mask:0xf bank_mask:0xf bound_ctrl:1
	v_pk_fma_f32 v[116:117], v[4:5], v[10:11], v[116:117] op_sel_hi:[1,0,1]
	v_add_f32_dpp v110, v110, v110 row_ror:1 row_mask:0xf bank_mask:0xf bound_ctrl:1
	v_add_f32_dpp v111, v111, v111 row_ror:1 row_mask:0xf bank_mask:0xf bound_ctrl:1
	v_pk_fma_f32 v[114:115], v[6:7], v[10:11], v[114:115] op_sel:[0,1,0]
	v_pk_fma_f32 v[0:1], v[110:111], v[16:17], v[38:39] op_sel_hi:[1,0,1]
	v_pk_fma_f32 v[2:3], v[110:111], v[16:17], v[82:83] op_sel:[0,1,0]
	v_pk_fma_f32 v[4:5], v[110:111], v[18:19], v[116:117] op_sel_hi:[1,0,1]
	v_pk_fma_f32 v[6:7], v[110:111], v[18:19], v[114:115] op_sel:[0,1,0]
	v_pk_mul_f32 v[112:113], v[0:1], v[24:25] op_sel_hi:[1,0]
	v_pk_fma_f32 v[112:113], v[2:3], v[24:25], v[112:113] op_sel:[0,1,0]
	v_pk_fma_f32 v[112:113], v[4:5], v[26:27], v[112:113] op_sel_hi:[1,0,1]
	v_pk_fma_f32 v[112:113], v[6:7], v[26:27], v[112:113] op_sel:[0,1,0]
	ds_write_b32 v119, v112 offset:4096
	ds_write_b32 v119, v113 offset:4160
	s_waitcnt lgkmcnt(2)
	v_pk_mul_f32 v[110:111], v[0:1], v[34:35] op_sel_hi:[1,0]
	v_pk_mul_f32 v[38:39], v[108:109], v[78:79] op_sel_hi:[1,0]
	v_pk_fma_f32 v[110:111], v[2:3], v[34:35], v[110:111] op_sel:[0,1,0]
	v_pk_mul_f32 v[82:83], v[108:109], v[78:79] op_sel:[0,1]
	v_pk_fma_f32 v[110:111], v[4:5], v[36:37], v[110:111] op_sel_hi:[1,0,1]
	v_pk_mul_f32 v[116:117], v[108:109], v[80:81] op_sel_hi:[1,0]
	v_pk_fma_f32 v[110:111], v[6:7], v[36:37], v[110:111] op_sel:[0,1,0]
	v_pk_mul_f32 v[114:115], v[108:109], v[80:81] op_sel:[0,1]
	ds_read_b128 v[12:15], v69 offset:30976
	ds_read_b128 v[20:23], v69 offset:31488
	ds_read_b64 v[28:29], v118 offset:32000
	ds_read_b128 v[8:11], v69 offset:30720
	ds_read_b128 v[16:19], v69 offset:31232
	ds_read_b128 v[24:27], v69 offset:31744
	v_add_f32_dpp v110, v110, v110 row_ror:8 row_mask:0xf bank_mask:0xf bound_ctrl:1
	v_add_f32_dpp v111, v111, v111 row_ror:8 row_mask:0xf bank_mask:0xf bound_ctrl:1
	v_pk_fma_f32 v[38:39], v[0:1], v[30:31], v[38:39] op_sel_hi:[1,0,1]
	v_add_f32_dpp v110, v110, v110 row_ror:4 row_mask:0xf bank_mask:0xf bound_ctrl:1
	v_add_f32_dpp v111, v111, v111 row_ror:4 row_mask:0xf bank_mask:0xf bound_ctrl:1
	v_pk_fma_f32 v[82:83], v[2:3], v[30:31], v[82:83] op_sel:[0,1,0]
	v_add_f32_dpp v110, v110, v110 row_ror:2 row_mask:0xf bank_mask:0xf bound_ctrl:1
	v_add_f32_dpp v111, v111, v111 row_ror:2 row_mask:0xf bank_mask:0xf bound_ctrl:1
	v_pk_fma_f32 v[116:117], v[4:5], v[32:33], v[116:117] op_sel_hi:[1,0,1]
	v_add_f32_dpp v110, v110, v110 row_ror:1 row_mask:0xf bank_mask:0xf bound_ctrl:1
	v_add_f32_dpp v111, v111, v111 row_ror:1 row_mask:0xf bank_mask:0xf bound_ctrl:1
	v_pk_fma_f32 v[114:115], v[6:7], v[32:33], v[114:115] op_sel:[0,1,0]
	v_pk_fma_f32 v[0:1], v[110:111], v[74:75], v[38:39] op_sel_hi:[1,0,1]
	v_pk_fma_f32 v[2:3], v[110:111], v[74:75], v[82:83] op_sel:[0,1,0]
	v_pk_fma_f32 v[4:5], v[110:111], v[76:77], v[116:117] op_sel_hi:[1,0,1]
	v_pk_fma_f32 v[6:7], v[110:111], v[76:77], v[114:115] op_sel:[0,1,0]
	v_pk_mul_f32 v[112:113], v[0:1], v[104:105] op_sel_hi:[1,0]
	v_pk_fma_f32 v[112:113], v[2:3], v[104:105], v[112:113] op_sel:[0,1,0]
	v_pk_fma_f32 v[112:113], v[4:5], v[106:107], v[112:113] op_sel_hi:[1,0,1]
	v_pk_fma_f32 v[112:113], v[6:7], v[106:107], v[112:113] op_sel:[0,1,0]
	ds_write_b32 v119, v112 offset:6144
	ds_write_b32 v119, v113 offset:6208
	s_waitcnt lgkmcnt(2)
	v_pk_mul_f32 v[110:111], v[0:1], v[12:13] op_sel_hi:[1,0]
	v_pk_mul_f32 v[38:39], v[28:29], v[20:21] op_sel_hi:[1,0]
	v_pk_fma_f32 v[110:111], v[2:3], v[12:13], v[110:111] op_sel:[0,1,0]
	v_pk_mul_f32 v[82:83], v[28:29], v[20:21] op_sel:[0,1]
	v_pk_fma_f32 v[110:111], v[4:5], v[14:15], v[110:111] op_sel_hi:[1,0,1]
	v_pk_mul_f32 v[116:117], v[28:29], v[22:23] op_sel_hi:[1,0]
	v_pk_fma_f32 v[110:111], v[6:7], v[14:15], v[110:111] op_sel:[0,1,0]
	v_pk_mul_f32 v[114:115], v[28:29], v[22:23] op_sel:[0,1]
	ds_read_b128 v[34:37], v69 offset:32512
	ds_read_b128 v[78:81], v69 offset:33024
	ds_read_b64 v[108:109], v118 offset:33536
	ds_read_b128 v[30:33], v69 offset:32256
	ds_read_b128 v[74:77], v69 offset:32768
	ds_read_b128 v[104:107], v69 offset:33280
	v_add_f32_dpp v110, v110, v110 row_ror:8 row_mask:0xf bank_mask:0xf bound_ctrl:1
	v_add_f32_dpp v111, v111, v111 row_ror:8 row_mask:0xf bank_mask:0xf bound_ctrl:1
	v_pk_fma_f32 v[38:39], v[0:1], v[8:9], v[38:39] op_sel_hi:[1,0,1]
	v_add_f32_dpp v110, v110, v110 row_ror:4 row_mask:0xf bank_mask:0xf bound_ctrl:1
	v_add_f32_dpp v111, v111, v111 row_ror:4 row_mask:0xf bank_mask:0xf bound_ctrl:1
	v_pk_fma_f32 v[82:83], v[2:3], v[8:9], v[82:83] op_sel:[0,1,0]
	v_add_f32_dpp v110, v110, v110 row_ror:2 row_mask:0xf bank_mask:0xf bound_ctrl:1
	v_add_f32_dpp v111, v111, v111 row_ror:2 row_mask:0xf bank_mask:0xf bound_ctrl:1
	v_pk_fma_f32 v[116:117], v[4:5], v[10:11], v[116:117] op_sel_hi:[1,0,1]
	v_add_f32_dpp v110, v110, v110 row_ror:1 row_mask:0xf bank_mask:0xf bound_ctrl:1
	v_add_f32_dpp v111, v111, v111 row_ror:1 row_mask:0xf bank_mask:0xf bound_ctrl:1
	v_pk_fma_f32 v[114:115], v[6:7], v[10:11], v[114:115] op_sel:[0,1,0]
	v_pk_fma_f32 v[0:1], v[110:111], v[16:17], v[38:39] op_sel_hi:[1,0,1]
	v_pk_fma_f32 v[2:3], v[110:111], v[16:17], v[82:83] op_sel:[0,1,0]
	v_pk_fma_f32 v[4:5], v[110:111], v[18:19], v[116:117] op_sel_hi:[1,0,1]
	v_pk_fma_f32 v[6:7], v[110:111], v[18:19], v[114:115] op_sel:[0,1,0]
	v_pk_mul_f32 v[112:113], v[0:1], v[24:25] op_sel_hi:[1,0]
	v_pk_fma_f32 v[112:113], v[2:3], v[24:25], v[112:113] op_sel:[0,1,0]
	v_pk_fma_f32 v[112:113], v[4:5], v[26:27], v[112:113] op_sel_hi:[1,0,1]
	v_pk_fma_f32 v[112:113], v[6:7], v[26:27], v[112:113] op_sel:[0,1,0]
	ds_write_b32 v119, v112 offset:8192
	ds_write_b32 v119, v113 offset:8256
	s_waitcnt lgkmcnt(2)
	v_pk_mul_f32 v[110:111], v[0:1], v[34:35] op_sel_hi:[1,0]
	v_pk_mul_f32 v[38:39], v[108:109], v[78:79] op_sel_hi:[1,0]
	v_pk_fma_f32 v[110:111], v[2:3], v[34:35], v[110:111] op_sel:[0,1,0]
	v_pk_mul_f32 v[82:83], v[108:109], v[78:79] op_sel:[0,1]
	v_pk_fma_f32 v[110:111], v[4:5], v[36:37], v[110:111] op_sel_hi:[1,0,1]
	v_pk_mul_f32 v[116:117], v[108:109], v[80:81] op_sel_hi:[1,0]
	v_pk_fma_f32 v[110:111], v[6:7], v[36:37], v[110:111] op_sel:[0,1,0]
	v_pk_mul_f32 v[114:115], v[108:109], v[80:81] op_sel:[0,1]
	ds_read_b128 v[12:15], v69 offset:34048
	ds_read_b128 v[20:23], v69 offset:34560
	ds_read_b64 v[28:29], v118 offset:35072
	ds_read_b128 v[8:11], v69 offset:33792
	ds_read_b128 v[16:19], v69 offset:34304
	ds_read_b128 v[24:27], v69 offset:34816
	v_add_f32_dpp v110, v110, v110 row_ror:8 row_mask:0xf bank_mask:0xf bound_ctrl:1
	v_add_f32_dpp v111, v111, v111 row_ror:8 row_mask:0xf bank_mask:0xf bound_ctrl:1
	v_pk_fma_f32 v[38:39], v[0:1], v[30:31], v[38:39] op_sel_hi:[1,0,1]
	v_add_f32_dpp v110, v110, v110 row_ror:4 row_mask:0xf bank_mask:0xf bound_ctrl:1
	v_add_f32_dpp v111, v111, v111 row_ror:4 row_mask:0xf bank_mask:0xf bound_ctrl:1
	v_pk_fma_f32 v[82:83], v[2:3], v[30:31], v[82:83] op_sel:[0,1,0]
	v_add_f32_dpp v110, v110, v110 row_ror:2 row_mask:0xf bank_mask:0xf bound_ctrl:1
	v_add_f32_dpp v111, v111, v111 row_ror:2 row_mask:0xf bank_mask:0xf bound_ctrl:1
	v_pk_fma_f32 v[116:117], v[4:5], v[32:33], v[116:117] op_sel_hi:[1,0,1]
	v_add_f32_dpp v110, v110, v110 row_ror:1 row_mask:0xf bank_mask:0xf bound_ctrl:1
	v_add_f32_dpp v111, v111, v111 row_ror:1 row_mask:0xf bank_mask:0xf bound_ctrl:1
	v_pk_fma_f32 v[114:115], v[6:7], v[32:33], v[114:115] op_sel:[0,1,0]
	v_pk_fma_f32 v[0:1], v[110:111], v[74:75], v[38:39] op_sel_hi:[1,0,1]
	v_pk_fma_f32 v[2:3], v[110:111], v[74:75], v[82:83] op_sel:[0,1,0]
	v_pk_fma_f32 v[4:5], v[110:111], v[76:77], v[116:117] op_sel_hi:[1,0,1]
	v_pk_fma_f32 v[6:7], v[110:111], v[76:77], v[114:115] op_sel:[0,1,0]
	v_pk_mul_f32 v[112:113], v[0:1], v[104:105] op_sel_hi:[1,0]
	v_pk_fma_f32 v[112:113], v[2:3], v[104:105], v[112:113] op_sel:[0,1,0]
	v_pk_fma_f32 v[112:113], v[4:5], v[106:107], v[112:113] op_sel_hi:[1,0,1]
	v_pk_fma_f32 v[112:113], v[6:7], v[106:107], v[112:113] op_sel:[0,1,0]
	ds_write_b32 v119, v112 offset:10240
	ds_write_b32 v119, v113 offset:10304
	s_waitcnt lgkmcnt(2)
	v_pk_mul_f32 v[110:111], v[0:1], v[12:13] op_sel_hi:[1,0]
	v_pk_mul_f32 v[38:39], v[28:29], v[20:21] op_sel_hi:[1,0]
	v_pk_fma_f32 v[110:111], v[2:3], v[12:13], v[110:111] op_sel:[0,1,0]
	v_pk_mul_f32 v[82:83], v[28:29], v[20:21] op_sel:[0,1]
	v_pk_fma_f32 v[110:111], v[4:5], v[14:15], v[110:111] op_sel_hi:[1,0,1]
	v_pk_mul_f32 v[116:117], v[28:29], v[22:23] op_sel_hi:[1,0]
	v_pk_fma_f32 v[110:111], v[6:7], v[14:15], v[110:111] op_sel:[0,1,0]
	v_pk_mul_f32 v[114:115], v[28:29], v[22:23] op_sel:[0,1]
	ds_read_b128 v[34:37], v69 offset:35584
	ds_read_b128 v[78:81], v69 offset:36096
	ds_read_b64 v[108:109], v118 offset:36608
	ds_read_b128 v[30:33], v69 offset:35328
	ds_read_b128 v[74:77], v69 offset:35840
	ds_read_b128 v[104:107], v69 offset:36352
	v_add_f32_dpp v110, v110, v110 row_ror:8 row_mask:0xf bank_mask:0xf bound_ctrl:1
	v_add_f32_dpp v111, v111, v111 row_ror:8 row_mask:0xf bank_mask:0xf bound_ctrl:1
	v_pk_fma_f32 v[38:39], v[0:1], v[8:9], v[38:39] op_sel_hi:[1,0,1]
	v_add_f32_dpp v110, v110, v110 row_ror:4 row_mask:0xf bank_mask:0xf bound_ctrl:1
	v_add_f32_dpp v111, v111, v111 row_ror:4 row_mask:0xf bank_mask:0xf bound_ctrl:1
	v_pk_fma_f32 v[82:83], v[2:3], v[8:9], v[82:83] op_sel:[0,1,0]
	v_add_f32_dpp v110, v110, v110 row_ror:2 row_mask:0xf bank_mask:0xf bound_ctrl:1
	v_add_f32_dpp v111, v111, v111 row_ror:2 row_mask:0xf bank_mask:0xf bound_ctrl:1
	v_pk_fma_f32 v[116:117], v[4:5], v[10:11], v[116:117] op_sel_hi:[1,0,1]
	v_add_f32_dpp v110, v110, v110 row_ror:1 row_mask:0xf bank_mask:0xf bound_ctrl:1
	v_add_f32_dpp v111, v111, v111 row_ror:1 row_mask:0xf bank_mask:0xf bound_ctrl:1
	v_pk_fma_f32 v[114:115], v[6:7], v[10:11], v[114:115] op_sel:[0,1,0]
	v_pk_fma_f32 v[0:1], v[110:111], v[16:17], v[38:39] op_sel_hi:[1,0,1]
	v_pk_fma_f32 v[2:3], v[110:111], v[16:17], v[82:83] op_sel:[0,1,0]
	v_pk_fma_f32 v[4:5], v[110:111], v[18:19], v[116:117] op_sel_hi:[1,0,1]
	v_pk_fma_f32 v[6:7], v[110:111], v[18:19], v[114:115] op_sel:[0,1,0]
	v_pk_mul_f32 v[112:113], v[0:1], v[24:25] op_sel_hi:[1,0]
	v_pk_fma_f32 v[112:113], v[2:3], v[24:25], v[112:113] op_sel:[0,1,0]
	v_pk_fma_f32 v[112:113], v[4:5], v[26:27], v[112:113] op_sel_hi:[1,0,1]
	v_pk_fma_f32 v[112:113], v[6:7], v[26:27], v[112:113] op_sel:[0,1,0]
	ds_write_b32 v119, v112 offset:12288
	ds_write_b32 v119, v113 offset:12352
	s_waitcnt lgkmcnt(2)
	v_pk_mul_f32 v[110:111], v[0:1], v[34:35] op_sel_hi:[1,0]
	v_pk_mul_f32 v[38:39], v[108:109], v[78:79] op_sel_hi:[1,0]
	v_pk_fma_f32 v[110:111], v[2:3], v[34:35], v[110:111] op_sel:[0,1,0]
	v_pk_mul_f32 v[82:83], v[108:109], v[78:79] op_sel:[0,1]
	v_pk_fma_f32 v[110:111], v[4:5], v[36:37], v[110:111] op_sel_hi:[1,0,1]
	v_pk_mul_f32 v[116:117], v[108:109], v[80:81] op_sel_hi:[1,0]
	v_pk_fma_f32 v[110:111], v[6:7], v[36:37], v[110:111] op_sel:[0,1,0]
	v_pk_mul_f32 v[114:115], v[108:109], v[80:81] op_sel:[0,1]
	ds_read_b128 v[12:15], v69 offset:37120
	ds_read_b128 v[20:23], v69 offset:37632
	ds_read_b64 v[28:29], v118 offset:38144
	ds_read_b128 v[8:11], v69 offset:36864
	ds_read_b128 v[16:19], v69 offset:37376
	ds_read_b128 v[24:27], v69 offset:37888
	v_add_f32_dpp v110, v110, v110 row_ror:8 row_mask:0xf bank_mask:0xf bound_ctrl:1
	v_add_f32_dpp v111, v111, v111 row_ror:8 row_mask:0xf bank_mask:0xf bound_ctrl:1
	v_pk_fma_f32 v[38:39], v[0:1], v[30:31], v[38:39] op_sel_hi:[1,0,1]
	v_add_f32_dpp v110, v110, v110 row_ror:4 row_mask:0xf bank_mask:0xf bound_ctrl:1
	v_add_f32_dpp v111, v111, v111 row_ror:4 row_mask:0xf bank_mask:0xf bound_ctrl:1
	v_pk_fma_f32 v[82:83], v[2:3], v[30:31], v[82:83] op_sel:[0,1,0]
	v_add_f32_dpp v110, v110, v110 row_ror:2 row_mask:0xf bank_mask:0xf bound_ctrl:1
	v_add_f32_dpp v111, v111, v111 row_ror:2 row_mask:0xf bank_mask:0xf bound_ctrl:1
	v_pk_fma_f32 v[116:117], v[4:5], v[32:33], v[116:117] op_sel_hi:[1,0,1]
	v_add_f32_dpp v110, v110, v110 row_ror:1 row_mask:0xf bank_mask:0xf bound_ctrl:1
	v_add_f32_dpp v111, v111, v111 row_ror:1 row_mask:0xf bank_mask:0xf bound_ctrl:1
	v_pk_fma_f32 v[114:115], v[6:7], v[32:33], v[114:115] op_sel:[0,1,0]
	v_pk_fma_f32 v[0:1], v[110:111], v[74:75], v[38:39] op_sel_hi:[1,0,1]
	v_pk_fma_f32 v[2:3], v[110:111], v[74:75], v[82:83] op_sel:[0,1,0]
	v_pk_fma_f32 v[4:5], v[110:111], v[76:77], v[116:117] op_sel_hi:[1,0,1]
	v_pk_fma_f32 v[6:7], v[110:111], v[76:77], v[114:115] op_sel:[0,1,0]
	v_pk_mul_f32 v[112:113], v[0:1], v[104:105] op_sel_hi:[1,0]
	v_pk_fma_f32 v[112:113], v[2:3], v[104:105], v[112:113] op_sel:[0,1,0]
	v_pk_fma_f32 v[112:113], v[4:5], v[106:107], v[112:113] op_sel_hi:[1,0,1]
	v_pk_fma_f32 v[112:113], v[6:7], v[106:107], v[112:113] op_sel:[0,1,0]
	ds_write_b32 v119, v112 offset:14336
	ds_write_b32 v119, v113 offset:14400
	s_waitcnt lgkmcnt(2)
	v_pk_mul_f32 v[110:111], v[0:1], v[12:13] op_sel_hi:[1,0]
	v_pk_mul_f32 v[38:39], v[28:29], v[20:21] op_sel_hi:[1,0]
	v_pk_fma_f32 v[110:111], v[2:3], v[12:13], v[110:111] op_sel:[0,1,0]
	v_pk_mul_f32 v[82:83], v[28:29], v[20:21] op_sel:[0,1]
	v_pk_fma_f32 v[110:111], v[4:5], v[14:15], v[110:111] op_sel_hi:[1,0,1]
	v_pk_mul_f32 v[116:117], v[28:29], v[22:23] op_sel_hi:[1,0]
	v_pk_fma_f32 v[110:111], v[6:7], v[14:15], v[110:111] op_sel:[0,1,0]
	v_pk_mul_f32 v[114:115], v[28:29], v[22:23] op_sel:[0,1]
	ds_read_b128 v[34:37], v69 offset:38656
	ds_read_b128 v[78:81], v69 offset:39168
	ds_read_b64 v[108:109], v118 offset:39680
	ds_read_b128 v[30:33], v69 offset:38400
	ds_read_b128 v[74:77], v69 offset:38912
	ds_read_b128 v[104:107], v69 offset:39424
	v_add_f32_dpp v110, v110, v110 row_ror:8 row_mask:0xf bank_mask:0xf bound_ctrl:1
	v_add_f32_dpp v111, v111, v111 row_ror:8 row_mask:0xf bank_mask:0xf bound_ctrl:1
	v_pk_fma_f32 v[38:39], v[0:1], v[8:9], v[38:39] op_sel_hi:[1,0,1]
	v_add_f32_dpp v110, v110, v110 row_ror:4 row_mask:0xf bank_mask:0xf bound_ctrl:1
	v_add_f32_dpp v111, v111, v111 row_ror:4 row_mask:0xf bank_mask:0xf bound_ctrl:1
	v_pk_fma_f32 v[82:83], v[2:3], v[8:9], v[82:83] op_sel:[0,1,0]
	v_add_f32_dpp v110, v110, v110 row_ror:2 row_mask:0xf bank_mask:0xf bound_ctrl:1
	v_add_f32_dpp v111, v111, v111 row_ror:2 row_mask:0xf bank_mask:0xf bound_ctrl:1
	v_pk_fma_f32 v[116:117], v[4:5], v[10:11], v[116:117] op_sel_hi:[1,0,1]
	v_add_f32_dpp v110, v110, v110 row_ror:1 row_mask:0xf bank_mask:0xf bound_ctrl:1
	v_add_f32_dpp v111, v111, v111 row_ror:1 row_mask:0xf bank_mask:0xf bound_ctrl:1
	v_pk_fma_f32 v[114:115], v[6:7], v[10:11], v[114:115] op_sel:[0,1,0]
	v_pk_fma_f32 v[0:1], v[110:111], v[16:17], v[38:39] op_sel_hi:[1,0,1]
	v_pk_fma_f32 v[2:3], v[110:111], v[16:17], v[82:83] op_sel:[0,1,0]
	v_pk_fma_f32 v[4:5], v[110:111], v[18:19], v[116:117] op_sel_hi:[1,0,1]
	v_pk_fma_f32 v[6:7], v[110:111], v[18:19], v[114:115] op_sel:[0,1,0]
	v_pk_mul_f32 v[112:113], v[0:1], v[24:25] op_sel_hi:[1,0]
	v_pk_fma_f32 v[112:113], v[2:3], v[24:25], v[112:113] op_sel:[0,1,0]
	v_pk_fma_f32 v[112:113], v[4:5], v[26:27], v[112:113] op_sel_hi:[1,0,1]
	v_pk_fma_f32 v[112:113], v[6:7], v[26:27], v[112:113] op_sel:[0,1,0]
	ds_write_b32 v119, v112 offset:16384
	ds_write_b32 v119, v113 offset:16448
	s_waitcnt lgkmcnt(2)
	v_pk_mul_f32 v[110:111], v[0:1], v[34:35] op_sel_hi:[1,0]
	v_pk_mul_f32 v[38:39], v[108:109], v[78:79] op_sel_hi:[1,0]
	v_pk_fma_f32 v[110:111], v[2:3], v[34:35], v[110:111] op_sel:[0,1,0]
	v_pk_mul_f32 v[82:83], v[108:109], v[78:79] op_sel:[0,1]
	v_pk_fma_f32 v[110:111], v[4:5], v[36:37], v[110:111] op_sel_hi:[1,0,1]
	v_pk_mul_f32 v[116:117], v[108:109], v[80:81] op_sel_hi:[1,0]
	v_pk_fma_f32 v[110:111], v[6:7], v[36:37], v[110:111] op_sel:[0,1,0]
	v_pk_mul_f32 v[114:115], v[108:109], v[80:81] op_sel:[0,1]
	ds_read_b128 v[12:15], v69 offset:40192
	ds_read_b128 v[20:23], v69 offset:40704
	ds_read_b64 v[28:29], v118 offset:41216
	ds_read_b128 v[8:11], v69 offset:39936
	ds_read_b128 v[16:19], v69 offset:40448
	ds_read_b128 v[24:27], v69 offset:40960
	v_add_f32_dpp v110, v110, v110 row_ror:8 row_mask:0xf bank_mask:0xf bound_ctrl:1
	v_add_f32_dpp v111, v111, v111 row_ror:8 row_mask:0xf bank_mask:0xf bound_ctrl:1
	v_pk_fma_f32 v[38:39], v[0:1], v[30:31], v[38:39] op_sel_hi:[1,0,1]
	v_add_f32_dpp v110, v110, v110 row_ror:4 row_mask:0xf bank_mask:0xf bound_ctrl:1
	v_add_f32_dpp v111, v111, v111 row_ror:4 row_mask:0xf bank_mask:0xf bound_ctrl:1
	v_pk_fma_f32 v[82:83], v[2:3], v[30:31], v[82:83] op_sel:[0,1,0]
	v_add_f32_dpp v110, v110, v110 row_ror:2 row_mask:0xf bank_mask:0xf bound_ctrl:1
	v_add_f32_dpp v111, v111, v111 row_ror:2 row_mask:0xf bank_mask:0xf bound_ctrl:1
	v_pk_fma_f32 v[116:117], v[4:5], v[32:33], v[116:117] op_sel_hi:[1,0,1]
	v_add_f32_dpp v110, v110, v110 row_ror:1 row_mask:0xf bank_mask:0xf bound_ctrl:1
	v_add_f32_dpp v111, v111, v111 row_ror:1 row_mask:0xf bank_mask:0xf bound_ctrl:1
	v_pk_fma_f32 v[114:115], v[6:7], v[32:33], v[114:115] op_sel:[0,1,0]
	v_pk_fma_f32 v[0:1], v[110:111], v[74:75], v[38:39] op_sel_hi:[1,0,1]
	v_pk_fma_f32 v[2:3], v[110:111], v[74:75], v[82:83] op_sel:[0,1,0]
	v_pk_fma_f32 v[4:5], v[110:111], v[76:77], v[116:117] op_sel_hi:[1,0,1]
	v_pk_fma_f32 v[6:7], v[110:111], v[76:77], v[114:115] op_sel:[0,1,0]
	v_pk_mul_f32 v[112:113], v[0:1], v[104:105] op_sel_hi:[1,0]
	v_pk_fma_f32 v[112:113], v[2:3], v[104:105], v[112:113] op_sel:[0,1,0]
	v_pk_fma_f32 v[112:113], v[4:5], v[106:107], v[112:113] op_sel_hi:[1,0,1]
	v_pk_fma_f32 v[112:113], v[6:7], v[106:107], v[112:113] op_sel:[0,1,0]
	ds_write_b32 v119, v112 offset:18432
	ds_write_b32 v119, v113 offset:18496
	s_waitcnt lgkmcnt(2)
	v_pk_mul_f32 v[110:111], v[0:1], v[12:13] op_sel_hi:[1,0]
	v_pk_mul_f32 v[38:39], v[28:29], v[20:21] op_sel_hi:[1,0]
	v_pk_fma_f32 v[110:111], v[2:3], v[12:13], v[110:111] op_sel:[0,1,0]
	v_pk_mul_f32 v[82:83], v[28:29], v[20:21] op_sel:[0,1]
	v_pk_fma_f32 v[110:111], v[4:5], v[14:15], v[110:111] op_sel_hi:[1,0,1]
	v_pk_mul_f32 v[116:117], v[28:29], v[22:23] op_sel_hi:[1,0]
	v_pk_fma_f32 v[110:111], v[6:7], v[14:15], v[110:111] op_sel:[0,1,0]
	v_pk_mul_f32 v[114:115], v[28:29], v[22:23] op_sel:[0,1]
	ds_read_b128 v[34:37], v69 offset:41728
	ds_read_b128 v[78:81], v69 offset:42240
	ds_read_b64 v[108:109], v118 offset:42752
	ds_read_b128 v[30:33], v69 offset:41472
	ds_read_b128 v[74:77], v69 offset:41984
	ds_read_b128 v[104:107], v69 offset:42496
	v_add_f32_dpp v110, v110, v110 row_ror:8 row_mask:0xf bank_mask:0xf bound_ctrl:1
	v_add_f32_dpp v111, v111, v111 row_ror:8 row_mask:0xf bank_mask:0xf bound_ctrl:1
	v_pk_fma_f32 v[38:39], v[0:1], v[8:9], v[38:39] op_sel_hi:[1,0,1]
	v_add_f32_dpp v110, v110, v110 row_ror:4 row_mask:0xf bank_mask:0xf bound_ctrl:1
	v_add_f32_dpp v111, v111, v111 row_ror:4 row_mask:0xf bank_mask:0xf bound_ctrl:1
	v_pk_fma_f32 v[82:83], v[2:3], v[8:9], v[82:83] op_sel:[0,1,0]
	v_add_f32_dpp v110, v110, v110 row_ror:2 row_mask:0xf bank_mask:0xf bound_ctrl:1
	v_add_f32_dpp v111, v111, v111 row_ror:2 row_mask:0xf bank_mask:0xf bound_ctrl:1
	v_pk_fma_f32 v[116:117], v[4:5], v[10:11], v[116:117] op_sel_hi:[1,0,1]
	v_add_f32_dpp v110, v110, v110 row_ror:1 row_mask:0xf bank_mask:0xf bound_ctrl:1
	v_add_f32_dpp v111, v111, v111 row_ror:1 row_mask:0xf bank_mask:0xf bound_ctrl:1
	v_pk_fma_f32 v[114:115], v[6:7], v[10:11], v[114:115] op_sel:[0,1,0]
	v_pk_fma_f32 v[0:1], v[110:111], v[16:17], v[38:39] op_sel_hi:[1,0,1]
	v_pk_fma_f32 v[2:3], v[110:111], v[16:17], v[82:83] op_sel:[0,1,0]
	v_pk_fma_f32 v[4:5], v[110:111], v[18:19], v[116:117] op_sel_hi:[1,0,1]
	v_pk_fma_f32 v[6:7], v[110:111], v[18:19], v[114:115] op_sel:[0,1,0]
	v_pk_mul_f32 v[112:113], v[0:1], v[24:25] op_sel_hi:[1,0]
	v_pk_fma_f32 v[112:113], v[2:3], v[24:25], v[112:113] op_sel:[0,1,0]
	v_pk_fma_f32 v[112:113], v[4:5], v[26:27], v[112:113] op_sel_hi:[1,0,1]
	v_pk_fma_f32 v[112:113], v[6:7], v[26:27], v[112:113] op_sel:[0,1,0]
	ds_write_b32 v119, v112 offset:20480
	ds_write_b32 v119, v113 offset:20544
	s_waitcnt lgkmcnt(2)
	v_pk_mul_f32 v[110:111], v[0:1], v[34:35] op_sel_hi:[1,0]
	v_pk_mul_f32 v[38:39], v[108:109], v[78:79] op_sel_hi:[1,0]
	v_pk_fma_f32 v[110:111], v[2:3], v[34:35], v[110:111] op_sel:[0,1,0]
	v_pk_mul_f32 v[82:83], v[108:109], v[78:79] op_sel:[0,1]
	v_pk_fma_f32 v[110:111], v[4:5], v[36:37], v[110:111] op_sel_hi:[1,0,1]
	v_pk_mul_f32 v[116:117], v[108:109], v[80:81] op_sel_hi:[1,0]
	v_pk_fma_f32 v[110:111], v[6:7], v[36:37], v[110:111] op_sel:[0,1,0]
	v_pk_mul_f32 v[114:115], v[108:109], v[80:81] op_sel:[0,1]
	ds_read_b128 v[12:15], v69 offset:43264
	ds_read_b128 v[20:23], v69 offset:43776
	ds_read_b64 v[28:29], v118 offset:44288
	ds_read_b128 v[8:11], v69 offset:43008
	ds_read_b128 v[16:19], v69 offset:43520
	ds_read_b128 v[24:27], v69 offset:44032
	v_add_f32_dpp v110, v110, v110 row_ror:8 row_mask:0xf bank_mask:0xf bound_ctrl:1
	v_add_f32_dpp v111, v111, v111 row_ror:8 row_mask:0xf bank_mask:0xf bound_ctrl:1
	v_pk_fma_f32 v[38:39], v[0:1], v[30:31], v[38:39] op_sel_hi:[1,0,1]
	v_add_f32_dpp v110, v110, v110 row_ror:4 row_mask:0xf bank_mask:0xf bound_ctrl:1
	v_add_f32_dpp v111, v111, v111 row_ror:4 row_mask:0xf bank_mask:0xf bound_ctrl:1
	v_pk_fma_f32 v[82:83], v[2:3], v[30:31], v[82:83] op_sel:[0,1,0]
	v_add_f32_dpp v110, v110, v110 row_ror:2 row_mask:0xf bank_mask:0xf bound_ctrl:1
	v_add_f32_dpp v111, v111, v111 row_ror:2 row_mask:0xf bank_mask:0xf bound_ctrl:1
	v_pk_fma_f32 v[116:117], v[4:5], v[32:33], v[116:117] op_sel_hi:[1,0,1]
	v_add_f32_dpp v110, v110, v110 row_ror:1 row_mask:0xf bank_mask:0xf bound_ctrl:1
	v_add_f32_dpp v111, v111, v111 row_ror:1 row_mask:0xf bank_mask:0xf bound_ctrl:1
	v_pk_fma_f32 v[114:115], v[6:7], v[32:33], v[114:115] op_sel:[0,1,0]
	v_pk_fma_f32 v[0:1], v[110:111], v[74:75], v[38:39] op_sel_hi:[1,0,1]
	v_pk_fma_f32 v[2:3], v[110:111], v[74:75], v[82:83] op_sel:[0,1,0]
	v_pk_fma_f32 v[4:5], v[110:111], v[76:77], v[116:117] op_sel_hi:[1,0,1]
	v_pk_fma_f32 v[6:7], v[110:111], v[76:77], v[114:115] op_sel:[0,1,0]
	v_pk_mul_f32 v[112:113], v[0:1], v[104:105] op_sel_hi:[1,0]
	v_pk_fma_f32 v[112:113], v[2:3], v[104:105], v[112:113] op_sel:[0,1,0]
	v_pk_fma_f32 v[112:113], v[4:5], v[106:107], v[112:113] op_sel_hi:[1,0,1]
	v_pk_fma_f32 v[112:113], v[6:7], v[106:107], v[112:113] op_sel:[0,1,0]
	ds_write_b32 v119, v112 offset:22528
	ds_write_b32 v119, v113 offset:22592
	s_waitcnt lgkmcnt(2)
	v_pk_mul_f32 v[110:111], v[0:1], v[12:13] op_sel_hi:[1,0]
	v_pk_mul_f32 v[38:39], v[28:29], v[20:21] op_sel_hi:[1,0]
	v_pk_fma_f32 v[110:111], v[2:3], v[12:13], v[110:111] op_sel:[0,1,0]
	v_pk_mul_f32 v[82:83], v[28:29], v[20:21] op_sel:[0,1]
	v_pk_fma_f32 v[110:111], v[4:5], v[14:15], v[110:111] op_sel_hi:[1,0,1]
	v_pk_mul_f32 v[116:117], v[28:29], v[22:23] op_sel_hi:[1,0]
	v_pk_fma_f32 v[110:111], v[6:7], v[14:15], v[110:111] op_sel:[0,1,0]
	v_pk_mul_f32 v[114:115], v[28:29], v[22:23] op_sel:[0,1]
	ds_read_b128 v[34:37], v69 offset:44800
	ds_read_b128 v[78:81], v69 offset:45312
	ds_read_b64 v[108:109], v118 offset:45824
	ds_read_b128 v[30:33], v69 offset:44544
	ds_read_b128 v[74:77], v69 offset:45056
	ds_read_b128 v[104:107], v69 offset:45568
	v_add_f32_dpp v110, v110, v110 row_ror:8 row_mask:0xf bank_mask:0xf bound_ctrl:1
	v_add_f32_dpp v111, v111, v111 row_ror:8 row_mask:0xf bank_mask:0xf bound_ctrl:1
	v_pk_fma_f32 v[38:39], v[0:1], v[8:9], v[38:39] op_sel_hi:[1,0,1]
	v_add_f32_dpp v110, v110, v110 row_ror:4 row_mask:0xf bank_mask:0xf bound_ctrl:1
	v_add_f32_dpp v111, v111, v111 row_ror:4 row_mask:0xf bank_mask:0xf bound_ctrl:1
	v_pk_fma_f32 v[82:83], v[2:3], v[8:9], v[82:83] op_sel:[0,1,0]
	v_add_f32_dpp v110, v110, v110 row_ror:2 row_mask:0xf bank_mask:0xf bound_ctrl:1
	v_add_f32_dpp v111, v111, v111 row_ror:2 row_mask:0xf bank_mask:0xf bound_ctrl:1
	v_pk_fma_f32 v[116:117], v[4:5], v[10:11], v[116:117] op_sel_hi:[1,0,1]
	v_add_f32_dpp v110, v110, v110 row_ror:1 row_mask:0xf bank_mask:0xf bound_ctrl:1
	v_add_f32_dpp v111, v111, v111 row_ror:1 row_mask:0xf bank_mask:0xf bound_ctrl:1
	v_pk_fma_f32 v[114:115], v[6:7], v[10:11], v[114:115] op_sel:[0,1,0]
	v_pk_fma_f32 v[0:1], v[110:111], v[16:17], v[38:39] op_sel_hi:[1,0,1]
	v_pk_fma_f32 v[2:3], v[110:111], v[16:17], v[82:83] op_sel:[0,1,0]
	v_pk_fma_f32 v[4:5], v[110:111], v[18:19], v[116:117] op_sel_hi:[1,0,1]
	v_pk_fma_f32 v[6:7], v[110:111], v[18:19], v[114:115] op_sel:[0,1,0]
	v_pk_mul_f32 v[112:113], v[0:1], v[24:25] op_sel_hi:[1,0]
	v_pk_fma_f32 v[112:113], v[2:3], v[24:25], v[112:113] op_sel:[0,1,0]
	v_pk_fma_f32 v[112:113], v[4:5], v[26:27], v[112:113] op_sel_hi:[1,0,1]
	v_pk_fma_f32 v[112:113], v[6:7], v[26:27], v[112:113] op_sel:[0,1,0]
	ds_write_b32 v119, v112 offset:24576
	ds_write_b32 v119, v113 offset:24640
	s_waitcnt lgkmcnt(2)
	v_pk_mul_f32 v[110:111], v[0:1], v[34:35] op_sel_hi:[1,0]
	v_pk_mul_f32 v[38:39], v[108:109], v[78:79] op_sel_hi:[1,0]
	v_pk_fma_f32 v[110:111], v[2:3], v[34:35], v[110:111] op_sel:[0,1,0]
	v_pk_mul_f32 v[82:83], v[108:109], v[78:79] op_sel:[0,1]
	v_pk_fma_f32 v[110:111], v[4:5], v[36:37], v[110:111] op_sel_hi:[1,0,1]
	v_pk_mul_f32 v[116:117], v[108:109], v[80:81] op_sel_hi:[1,0]
	v_pk_fma_f32 v[110:111], v[6:7], v[36:37], v[110:111] op_sel:[0,1,0]
	v_pk_mul_f32 v[114:115], v[108:109], v[80:81] op_sel:[0,1]
	ds_read_b128 v[12:15], v69 offset:46336
	ds_read_b128 v[20:23], v69 offset:46848
	ds_read_b64 v[28:29], v118 offset:47360
	ds_read_b128 v[8:11], v69 offset:46080
	ds_read_b128 v[16:19], v69 offset:46592
	ds_read_b128 v[24:27], v69 offset:47104
	v_add_f32_dpp v110, v110, v110 row_ror:8 row_mask:0xf bank_mask:0xf bound_ctrl:1
	v_add_f32_dpp v111, v111, v111 row_ror:8 row_mask:0xf bank_mask:0xf bound_ctrl:1
	v_pk_fma_f32 v[38:39], v[0:1], v[30:31], v[38:39] op_sel_hi:[1,0,1]
	v_add_f32_dpp v110, v110, v110 row_ror:4 row_mask:0xf bank_mask:0xf bound_ctrl:1
	v_add_f32_dpp v111, v111, v111 row_ror:4 row_mask:0xf bank_mask:0xf bound_ctrl:1
	v_pk_fma_f32 v[82:83], v[2:3], v[30:31], v[82:83] op_sel:[0,1,0]
	v_add_f32_dpp v110, v110, v110 row_ror:2 row_mask:0xf bank_mask:0xf bound_ctrl:1
	v_add_f32_dpp v111, v111, v111 row_ror:2 row_mask:0xf bank_mask:0xf bound_ctrl:1
	v_pk_fma_f32 v[116:117], v[4:5], v[32:33], v[116:117] op_sel_hi:[1,0,1]
	v_add_f32_dpp v110, v110, v110 row_ror:1 row_mask:0xf bank_mask:0xf bound_ctrl:1
	v_add_f32_dpp v111, v111, v111 row_ror:1 row_mask:0xf bank_mask:0xf bound_ctrl:1
	v_pk_fma_f32 v[114:115], v[6:7], v[32:33], v[114:115] op_sel:[0,1,0]
	v_pk_fma_f32 v[0:1], v[110:111], v[74:75], v[38:39] op_sel_hi:[1,0,1]
	v_pk_fma_f32 v[2:3], v[110:111], v[74:75], v[82:83] op_sel:[0,1,0]
	v_pk_fma_f32 v[4:5], v[110:111], v[76:77], v[116:117] op_sel_hi:[1,0,1]
	v_pk_fma_f32 v[6:7], v[110:111], v[76:77], v[114:115] op_sel:[0,1,0]
	v_pk_mul_f32 v[112:113], v[0:1], v[104:105] op_sel_hi:[1,0]
	v_pk_fma_f32 v[112:113], v[2:3], v[104:105], v[112:113] op_sel:[0,1,0]
	v_pk_fma_f32 v[112:113], v[4:5], v[106:107], v[112:113] op_sel_hi:[1,0,1]
	v_pk_fma_f32 v[112:113], v[6:7], v[106:107], v[112:113] op_sel:[0,1,0]
	ds_write_b32 v119, v112 offset:26624
	ds_write_b32 v119, v113 offset:26688
	s_waitcnt lgkmcnt(2)
	v_pk_mul_f32 v[110:111], v[0:1], v[12:13] op_sel_hi:[1,0]
	v_pk_mul_f32 v[38:39], v[28:29], v[20:21] op_sel_hi:[1,0]
	v_pk_fma_f32 v[110:111], v[2:3], v[12:13], v[110:111] op_sel:[0,1,0]
	v_pk_mul_f32 v[82:83], v[28:29], v[20:21] op_sel:[0,1]
	v_pk_fma_f32 v[110:111], v[4:5], v[14:15], v[110:111] op_sel_hi:[1,0,1]
	v_pk_mul_f32 v[116:117], v[28:29], v[22:23] op_sel_hi:[1,0]
	v_pk_fma_f32 v[110:111], v[6:7], v[14:15], v[110:111] op_sel:[0,1,0]
	v_pk_mul_f32 v[114:115], v[28:29], v[22:23] op_sel:[0,1]
	ds_read_b128 v[34:37], v69 offset:47872
	ds_read_b128 v[78:81], v69 offset:48384
	ds_read_b64 v[108:109], v118 offset:48896
	ds_read_b128 v[30:33], v69 offset:47616
	ds_read_b128 v[74:77], v69 offset:48128
	ds_read_b128 v[104:107], v69 offset:48640
	v_add_f32_dpp v110, v110, v110 row_ror:8 row_mask:0xf bank_mask:0xf bound_ctrl:1
	v_add_f32_dpp v111, v111, v111 row_ror:8 row_mask:0xf bank_mask:0xf bound_ctrl:1
	v_pk_fma_f32 v[38:39], v[0:1], v[8:9], v[38:39] op_sel_hi:[1,0,1]
	v_add_f32_dpp v110, v110, v110 row_ror:4 row_mask:0xf bank_mask:0xf bound_ctrl:1
	v_add_f32_dpp v111, v111, v111 row_ror:4 row_mask:0xf bank_mask:0xf bound_ctrl:1
	v_pk_fma_f32 v[82:83], v[2:3], v[8:9], v[82:83] op_sel:[0,1,0]
	v_add_f32_dpp v110, v110, v110 row_ror:2 row_mask:0xf bank_mask:0xf bound_ctrl:1
	v_add_f32_dpp v111, v111, v111 row_ror:2 row_mask:0xf bank_mask:0xf bound_ctrl:1
	v_pk_fma_f32 v[116:117], v[4:5], v[10:11], v[116:117] op_sel_hi:[1,0,1]
	v_add_f32_dpp v110, v110, v110 row_ror:1 row_mask:0xf bank_mask:0xf bound_ctrl:1
	v_add_f32_dpp v111, v111, v111 row_ror:1 row_mask:0xf bank_mask:0xf bound_ctrl:1
	v_pk_fma_f32 v[114:115], v[6:7], v[10:11], v[114:115] op_sel:[0,1,0]
	v_pk_fma_f32 v[0:1], v[110:111], v[16:17], v[38:39] op_sel_hi:[1,0,1]
	v_pk_fma_f32 v[2:3], v[110:111], v[16:17], v[82:83] op_sel:[0,1,0]
	v_pk_fma_f32 v[4:5], v[110:111], v[18:19], v[116:117] op_sel_hi:[1,0,1]
	v_pk_fma_f32 v[6:7], v[110:111], v[18:19], v[114:115] op_sel:[0,1,0]
	v_pk_mul_f32 v[112:113], v[0:1], v[24:25] op_sel_hi:[1,0]
	v_pk_fma_f32 v[112:113], v[2:3], v[24:25], v[112:113] op_sel:[0,1,0]
	v_pk_fma_f32 v[112:113], v[4:5], v[26:27], v[112:113] op_sel_hi:[1,0,1]
	v_pk_fma_f32 v[112:113], v[6:7], v[26:27], v[112:113] op_sel:[0,1,0]
	ds_write_b32 v119, v112 offset:28672
	ds_write_b32 v119, v113 offset:28736
	s_waitcnt lgkmcnt(2)
	v_pk_mul_f32 v[110:111], v[0:1], v[34:35] op_sel_hi:[1,0]
	v_pk_mul_f32 v[38:39], v[108:109], v[78:79] op_sel_hi:[1,0]
	v_pk_fma_f32 v[110:111], v[2:3], v[34:35], v[110:111] op_sel:[0,1,0]
	v_pk_mul_f32 v[82:83], v[108:109], v[78:79] op_sel:[0,1]
	v_pk_fma_f32 v[110:111], v[4:5], v[36:37], v[110:111] op_sel_hi:[1,0,1]
	v_pk_mul_f32 v[116:117], v[108:109], v[80:81] op_sel_hi:[1,0]
	v_pk_fma_f32 v[110:111], v[6:7], v[36:37], v[110:111] op_sel:[0,1,0]
	v_pk_mul_f32 v[114:115], v[108:109], v[80:81] op_sel:[0,1]
	s_nop 0
	v_add_f32_dpp v110, v110, v110 row_ror:8 row_mask:0xf bank_mask:0xf bound_ctrl:1
	v_add_f32_dpp v111, v111, v111 row_ror:8 row_mask:0xf bank_mask:0xf bound_ctrl:1
	v_pk_fma_f32 v[38:39], v[0:1], v[30:31], v[38:39] op_sel_hi:[1,0,1]
	v_add_f32_dpp v110, v110, v110 row_ror:4 row_mask:0xf bank_mask:0xf bound_ctrl:1
	v_add_f32_dpp v111, v111, v111 row_ror:4 row_mask:0xf bank_mask:0xf bound_ctrl:1
	v_pk_fma_f32 v[82:83], v[2:3], v[30:31], v[82:83] op_sel:[0,1,0]
	v_add_f32_dpp v110, v110, v110 row_ror:2 row_mask:0xf bank_mask:0xf bound_ctrl:1
	v_add_f32_dpp v111, v111, v111 row_ror:2 row_mask:0xf bank_mask:0xf bound_ctrl:1
	v_pk_fma_f32 v[116:117], v[4:5], v[32:33], v[116:117] op_sel_hi:[1,0,1]
	v_add_f32_dpp v110, v110, v110 row_ror:1 row_mask:0xf bank_mask:0xf bound_ctrl:1
	v_add_f32_dpp v111, v111, v111 row_ror:1 row_mask:0xf bank_mask:0xf bound_ctrl:1
	v_pk_fma_f32 v[114:115], v[6:7], v[32:33], v[114:115] op_sel:[0,1,0]
	v_pk_fma_f32 v[0:1], v[110:111], v[74:75], v[38:39] op_sel_hi:[1,0,1]
	v_pk_fma_f32 v[2:3], v[110:111], v[74:75], v[82:83] op_sel:[0,1,0]
	v_pk_fma_f32 v[4:5], v[110:111], v[76:77], v[116:117] op_sel_hi:[1,0,1]
	v_pk_fma_f32 v[6:7], v[110:111], v[76:77], v[114:115] op_sel:[0,1,0]
	v_pk_mul_f32 v[112:113], v[0:1], v[104:105] op_sel_hi:[1,0]
	v_pk_fma_f32 v[112:113], v[2:3], v[104:105], v[112:113] op_sel:[0,1,0]
	v_pk_fma_f32 v[112:113], v[4:5], v[106:107], v[112:113] op_sel_hi:[1,0,1]
	v_pk_fma_f32 v[112:113], v[6:7], v[106:107], v[112:113] op_sel:[0,1,0]
	ds_write_b32 v119, v112 offset:30720
	ds_write_b32 v119, v113 offset:30784
	s_setprio 0
	s_branch .LBB0_140
